# Griffin items at wave priority 2 (reset on leaving the Griffin loop) on top of v32
# speedup vs baseline: 1.0176x; 1.0176x over previous
.LBB0_476:
	s_or_b64 exec, exec, s[14:15]
	s_waitcnt lgkmcnt(0)
	s_barrier
	ds_read_b32 v2, v242
	s_mov_b64 s[14:15], -1
	s_waitcnt lgkmcnt(0)
	v_cmp_lt_i32_e32 vcc, s36, v2
	v_readfirstlane_b32 s23, v2
	s_cbranch_vccnz .LBB0_471
	s_setprio 2
	s_load_dwordx16 s[60:75], s[0:1], 0x40
	s_bfe_u32 s27, s23, 0x30002
	s_lshl_b32 s24, s27, 6
	v_or_b32_e32 v148, s24, v229
	s_waitcnt lgkmcnt(0)
	v_lshl_add_u64 v[2:3], v[148:149], 2, s[68:69]
	s_barrier
	global_load_dword v2, v[2:3], off
	v_readfirstlane_b32 s25, v226
	s_waitcnt vmcnt(0)
	ds_write_b32 v230, v2 offset:8320
	s_and_saveexec_b64 s[14:15], s[4:5]
	s_cbranch_execz .LBB0_479
	s_load_dwordx16 s[60:75], s[0:1], 0x40
	v_or_b32_e32 v148, s24, v1
	s_waitcnt lgkmcnt(0)
	v_lshl_add_u64 v[2:3], v[148:149], 2, s[70:71]
	global_load_dword v2, v[2:3], off
	s_waitcnt vmcnt(0)
	ds_write_b32 v230, v2 offset:9344
